# FFN2-down epilogue: residual loads hoisted (one wait) + DPP exchange so each f32 store writes 8 full 128B rows (on v24)
# baseline (speedup 1.0000x reference)
;     __device__ __forceinline__ void operator()(const AccT& acc, const Unit& u, int wr, int wc, int fr, int fq) const {
;     ...
;                 const int row = row0 + ai * HALF + m * 16; float sq = 0.f;
; #pragma unroll
;                 for (int bj = 0; bj < 2; ++bj) {
;                     const size_t off = (size_t)row * DM + col0 + bj * HALF;
;                     f32x4 r0, r1;
;                     if (RES_BF16) { float f[8]; unpack8(*(const u32x4*)(resb + off), f); r0 = (f32x4){f[0], f[1], f[2], f[3]}; r1 = (f32x4){f[4], f[5], f[6], f[7]}; }
;                     else { r0 = *(const f32x4*)(res + off); r1 = *(const f32x4*)(res + off + 4); }
;                     const f32x4 v0 = r0 + acc[ai][bj][m][0] * alpha, v1 = r1 + acc[ai][bj][m][1] * alpha;
;                     if (WRITE_F32) { *(f32x4*)(out + off) = v0; *(f32x4*)(out + off + 4) = v1; }
.LBB0_1641:
	s_mov_b32 s94, 0x00ff00ff
	s_mov_b32 s95, 0x00ff00ff
	v_mov_b32_e32 v248, 0xffff8010
	v_mov_b32_e32 v249, -1
	v_mov_b32_e32 v250, 0x8010
	v_mov_b32_e32 v251, 0
	v_cndmask_b32_e64 v248, v248, 0, s[94:95]
	v_cndmask_b32_e64 v249, v249, 0, s[94:95]
	v_cndmask_b32_e64 v250, 0, v250, s[94:95]
	v_lshl_add_u32 v148, s50, 8, v150
	v_lshl_or_b32 v146, s51, 8, v152
	v_ashrrev_i32_e32 v149, 31, v148
	v_ashrrev_i32_e32 v147, 31, v146
	v_lshlrev_b64 v[144:145], 10, v[148:149]
	v_lshl_add_u64 v[144:145], v[144:145], 0, v[146:147]
	v_lshlrev_b64 v[160:161], 1, v[144:145]
	v_lshl_add_u64 v[156:157], s[46:47], 0, v[160:161]
	s_mov_b32 s98, 0x8000
	s_mov_b32 s99, 0
	s_mov_b32 s100, 0x40000
	s_mov_b32 s101, 0
	v_lshl_add_u64 v[168:169], v[156:157], 0, s[98:99]
	v_lshl_add_u64 v[170:171], v[168:169], 0, s[98:99]
	v_lshl_add_u64 v[172:173], v[170:171], 0, s[98:99]
	v_lshl_add_u64 v[174:175], v[156:157], 0, s[100:101]
	v_lshl_add_u64 v[176:177], v[174:175], 0, s[98:99]
	v_lshl_add_u64 v[178:179], v[176:177], 0, s[98:99]
	v_lshl_add_u64 v[180:181], v[178:179], 0, s[98:99]
	global_load_dwordx4 v[184:187], v[156:157], off
	global_load_dwordx4 v[188:191], v[156:157], off offset:256
	global_load_dwordx4 v[192:195], v[168:169], off
	global_load_dwordx4 v[196:199], v[168:169], off offset:256
	global_load_dwordx4 v[200:203], v[170:171], off
	global_load_dwordx4 v[204:207], v[170:171], off offset:256
	global_load_dwordx4 v[208:211], v[172:173], off
	global_load_dwordx4 v[212:215], v[172:173], off offset:256
	global_load_dwordx4 v[216:219], v[174:175], off
	global_load_dwordx4 v[220:223], v[174:175], off offset:256
	global_load_dwordx4 v[224:227], v[176:177], off
	global_load_dwordx4 v[228:231], v[176:177], off offset:256
	global_load_dwordx4 v[232:235], v[178:179], off
	global_load_dwordx4 v[236:239], v[178:179], off offset:256
	global_load_dwordx4 v[240:243], v[180:181], off
	global_load_dwordx4 v[244:247], v[180:181], off offset:256
	s_waitcnt vmcnt(0)
	s_nop 1
	v_mov_b64_e32 v[156:157], v[184:185]
	v_mov_b64_e32 v[158:159], v[186:187]
	v_lshl_add_u64 v[162:163], v[144:145], 2, s[68:69]
	v_or_b32_e32 v160, 0x100, v160
	v_lshl_add_u64 v[160:161], s[46:47], 0, v[160:161]
	s_and_b64 vcc, exec, s[0:1]
	s_mov_b64 s[0:1], -1
	v_lshlrev_b32_e32 v164, 16, v156
	v_and_b32_e32 v165, 0xffff0000, v156
	v_lshlrev_b32_e32 v156, 16, v157
	v_and_b32_e32 v157, 0xffff0000, v157
	v_lshlrev_b32_e32 v166, 16, v158
	v_and_b32_e32 v167, 0xffff0000, v158
	v_lshlrev_b32_e32 v158, 16, v159
	v_and_b32_e32 v159, 0xffff0000, v159
	v_pk_fma_f32 v[126:127], v[126:127], 0.5, v[156:157] op_sel_hi:[1,0,1]
	v_pk_fma_f32 v[124:125], v[124:125], 0.5, v[164:165] op_sel_hi:[1,0,1]
	v_pk_fma_f32 v[122:123], v[122:123], 0.5, v[158:159] op_sel_hi:[1,0,1]
	v_pk_fma_f32 v[120:121], v[120:121], 0.5, v[166:167] op_sel_hi:[1,0,1]
	s_nop 1
	v_mov_b32_dpp v168, v120 row_ror:8 row_mask:0xf bank_mask:0xf
	v_mov_b32_dpp v169, v121 row_ror:8 row_mask:0xf bank_mask:0xf
	v_mov_b32_dpp v170, v122 row_ror:8 row_mask:0xf bank_mask:0xf
	v_mov_b32_dpp v171, v123 row_ror:8 row_mask:0xf bank_mask:0xf
	v_lshl_add_u64 v[180:181], v[162:163], 0, v[248:249]
	v_lshl_add_u64 v[182:183], v[162:163], 0, v[250:251]
	v_cndmask_b32_e64 v172, v168, v124, s[94:95]
	v_cndmask_b32_e64 v173, v169, v125, s[94:95]
	v_cndmask_b32_e64 v174, v170, v126, s[94:95]
	v_cndmask_b32_e64 v175, v171, v127, s[94:95]
	v_cndmask_b32_e64 v176, v124, v168, s[94:95]
	v_cndmask_b32_e64 v177, v125, v169, s[94:95]
	v_cndmask_b32_e64 v178, v126, v170, s[94:95]
	v_cndmask_b32_e64 v179, v127, v171, s[94:95]
	global_store_dwordx4 v[180:181], v[172:175], off
	global_store_dwordx4 v[182:183], v[176:179], off
	s_nop 1
	v_mov_b64_e32 v[120:121], v[188:189]
	v_mov_b64_e32 v[122:123], v[190:191]
	v_or_b32_e32 v124, 16, v148
	v_ashrrev_i32_e32 v125, 31, v124
	v_lshlrev_b64 v[124:125], 10, v[124:125]
	v_lshl_add_u64 v[124:125], v[124:125], 0, v[146:147]
	v_lshlrev_b64 v[126:127], 1, v[124:125]
	v_lshl_add_u64 v[156:157], s[46:47], 0, v[126:127]
	v_or_b32_e32 v126, 0x100, v126
	v_lshlrev_b32_e32 v158, 16, v120
	v_and_b32_e32 v159, 0xffff0000, v120
	v_lshlrev_b32_e32 v120, 16, v121
	v_and_b32_e32 v121, 0xffff0000, v121
	v_lshlrev_b32_e32 v160, 16, v122
	v_and_b32_e32 v161, 0xffff0000, v122
	v_lshlrev_b32_e32 v122, 16, v123
	v_and_b32_e32 v123, 0xffff0000, v123
	v_pk_fma_f32 v[118:119], v[118:119], 0.5, v[120:121] op_sel_hi:[1,0,1]
	v_pk_fma_f32 v[116:117], v[116:117], 0.5, v[158:159] op_sel_hi:[1,0,1]
	v_pk_fma_f32 v[114:115], v[114:115], 0.5, v[122:123] op_sel_hi:[1,0,1]
	v_pk_fma_f32 v[112:113], v[112:113], 0.5, v[160:161] op_sel_hi:[1,0,1]
	s_nop 1
	v_mov_b32_dpp v168, v112 row_ror:8 row_mask:0xf bank_mask:0xf
	v_mov_b32_dpp v169, v113 row_ror:8 row_mask:0xf bank_mask:0xf
	v_mov_b32_dpp v170, v114 row_ror:8 row_mask:0xf bank_mask:0xf
	v_mov_b32_dpp v171, v115 row_ror:8 row_mask:0xf bank_mask:0xf
	v_lshl_add_u64 v[180:181], v[162:163], 0, v[248:249]
	v_lshl_add_u64 v[182:183], v[162:163], 0, v[250:251]
	v_cndmask_b32_e64 v172, v168, v116, s[94:95]
	v_cndmask_b32_e64 v173, v169, v117, s[94:95]
	v_cndmask_b32_e64 v174, v170, v118, s[94:95]
	v_cndmask_b32_e64 v175, v171, v119, s[94:95]
	v_cndmask_b32_e64 v176, v116, v168, s[94:95]
	v_cndmask_b32_e64 v177, v117, v169, s[94:95]
	v_cndmask_b32_e64 v178, v118, v170, s[94:95]
	v_cndmask_b32_e64 v179, v119, v171, s[94:95]
	global_store_dwordx4 v[180:181], v[172:175], off offset:512
	global_store_dwordx4 v[182:183], v[176:179], off offset:512
	s_nop 1
	v_mov_b64_e32 v[112:113], v[192:193]
	v_mov_b64_e32 v[114:115], v[194:195]
	v_lshl_add_u64 v[116:117], v[124:125], 2, s[68:69]
	v_lshl_add_u64 v[118:119], s[46:47], 0, v[126:127]
;     __device__ __forceinline__ void operator()(const AccT& acc, const Unit& u, int wr, int wc, int fr, int fq) const {
;     ...
;                 const int row = row0 + ai * HALF + m * 16; float sq = 0.f;
; #pragma unroll
;                 for (int bj = 0; bj < 2; ++bj) {
;                     const size_t off = (size_t)row * DM + col0 + bj * HALF;
;                     f32x4 r0, r1;
;                     if (RES_BF16) { float f[8]; unpack8(*(const u32x4*)(resb + off), f); r0 = (f32x4){f[0], f[1], f[2], f[3]}; r1 = (f32x4){f[4], f[5], f[6], f[7]}; }
;                     else { r0 = *(const f32x4*)(res + off); r1 = *(const f32x4*)(res + off + 4); }
;                     const f32x4 v0 = r0 + acc[ai][bj][m][0] * alpha, v1 = r1 + acc[ai][bj][m][1] * alpha;
;                     if (WRITE_F32) { *(f32x4*)(out + off) = v0; *(f32x4*)(out + off + 4) = v1; }
	v_lshlrev_b32_e32 v120, 16, v112
	v_and_b32_e32 v121, 0xffff0000, v112
	v_lshlrev_b32_e32 v112, 16, v113
	v_and_b32_e32 v113, 0xffff0000, v113
	v_lshlrev_b32_e32 v122, 16, v114
	v_and_b32_e32 v123, 0xffff0000, v114
	v_lshlrev_b32_e32 v114, 16, v115
	v_and_b32_e32 v115, 0xffff0000, v115
	v_pk_fma_f32 v[110:111], v[110:111], 0.5, v[112:113] op_sel_hi:[1,0,1]
	v_pk_fma_f32 v[108:109], v[108:109], 0.5, v[120:121] op_sel_hi:[1,0,1]
	v_pk_fma_f32 v[106:107], v[106:107], 0.5, v[114:115] op_sel_hi:[1,0,1]
	v_pk_fma_f32 v[104:105], v[104:105], 0.5, v[122:123] op_sel_hi:[1,0,1]
	s_nop 1
	v_mov_b32_dpp v168, v104 row_ror:8 row_mask:0xf bank_mask:0xf
	v_mov_b32_dpp v169, v105 row_ror:8 row_mask:0xf bank_mask:0xf
	v_mov_b32_dpp v170, v106 row_ror:8 row_mask:0xf bank_mask:0xf
	v_mov_b32_dpp v171, v107 row_ror:8 row_mask:0xf bank_mask:0xf
	v_lshl_add_u64 v[180:181], v[116:117], 0, v[248:249]
	v_lshl_add_u64 v[182:183], v[116:117], 0, v[250:251]
	v_cndmask_b32_e64 v172, v168, v108, s[94:95]
	v_cndmask_b32_e64 v173, v169, v109, s[94:95]
	v_cndmask_b32_e64 v174, v170, v110, s[94:95]
	v_cndmask_b32_e64 v175, v171, v111, s[94:95]
	v_cndmask_b32_e64 v176, v108, v168, s[94:95]
	v_cndmask_b32_e64 v177, v109, v169, s[94:95]
	v_cndmask_b32_e64 v178, v110, v170, s[94:95]
	v_cndmask_b32_e64 v179, v111, v171, s[94:95]
	global_store_dwordx4 v[180:181], v[172:175], off
	global_store_dwordx4 v[182:183], v[176:179], off
	s_nop 1
	v_mov_b64_e32 v[104:105], v[196:197]
	v_mov_b64_e32 v[106:107], v[198:199]
	v_or_b32_e32 v108, 32, v148
	v_ashrrev_i32_e32 v109, 31, v108
	v_lshlrev_b64 v[108:109], 10, v[108:109]
	v_lshl_add_u64 v[108:109], v[108:109], 0, v[146:147]
	v_lshlrev_b64 v[110:111], 1, v[108:109]
	v_lshl_add_u64 v[112:113], s[46:47], 0, v[110:111]
	v_or_b32_e32 v110, 0x100, v110
	v_lshlrev_b32_e32 v114, 16, v104
	v_and_b32_e32 v115, 0xffff0000, v104
	v_lshlrev_b32_e32 v104, 16, v105
	v_and_b32_e32 v105, 0xffff0000, v105
	v_lshlrev_b32_e32 v118, 16, v106
	v_and_b32_e32 v119, 0xffff0000, v106
	v_lshlrev_b32_e32 v106, 16, v107
	v_and_b32_e32 v107, 0xffff0000, v107
	v_pk_fma_f32 v[102:103], v[102:103], 0.5, v[104:105] op_sel_hi:[1,0,1]
	v_pk_fma_f32 v[100:101], v[100:101], 0.5, v[114:115] op_sel_hi:[1,0,1]
	v_pk_fma_f32 v[98:99], v[98:99], 0.5, v[106:107] op_sel_hi:[1,0,1]
	v_pk_fma_f32 v[96:97], v[96:97], 0.5, v[118:119] op_sel_hi:[1,0,1]
	s_nop 1
	v_mov_b32_dpp v168, v96 row_ror:8 row_mask:0xf bank_mask:0xf
	v_mov_b32_dpp v169, v97 row_ror:8 row_mask:0xf bank_mask:0xf
	v_mov_b32_dpp v170, v98 row_ror:8 row_mask:0xf bank_mask:0xf
	v_mov_b32_dpp v171, v99 row_ror:8 row_mask:0xf bank_mask:0xf
	v_lshl_add_u64 v[180:181], v[116:117], 0, v[248:249]
	v_lshl_add_u64 v[182:183], v[116:117], 0, v[250:251]
	v_cndmask_b32_e64 v172, v168, v100, s[94:95]
	v_cndmask_b32_e64 v173, v169, v101, s[94:95]
	v_cndmask_b32_e64 v174, v170, v102, s[94:95]
	v_cndmask_b32_e64 v175, v171, v103, s[94:95]
	v_cndmask_b32_e64 v176, v100, v168, s[94:95]
	v_cndmask_b32_e64 v177, v101, v169, s[94:95]
	v_cndmask_b32_e64 v178, v102, v170, s[94:95]
	v_cndmask_b32_e64 v179, v103, v171, s[94:95]
	global_store_dwordx4 v[180:181], v[172:175], off offset:512
	global_store_dwordx4 v[182:183], v[176:179], off offset:512
	s_nop 1
	v_mov_b64_e32 v[96:97], v[200:201]
	v_mov_b64_e32 v[98:99], v[202:203]
	v_lshl_add_u64 v[100:101], v[108:109], 2, s[68:69]
	v_lshl_add_u64 v[102:103], s[46:47], 0, v[110:111]
	v_lshlrev_b32_e32 v104, 16, v96
	v_and_b32_e32 v105, 0xffff0000, v96
	v_lshlrev_b32_e32 v96, 16, v97
	v_and_b32_e32 v97, 0xffff0000, v97
	v_lshlrev_b32_e32 v106, 16, v98
	v_and_b32_e32 v107, 0xffff0000, v98
	v_lshlrev_b32_e32 v98, 16, v99
	v_and_b32_e32 v99, 0xffff0000, v99
	v_pk_fma_f32 v[94:95], v[94:95], 0.5, v[96:97] op_sel_hi:[1,0,1]
	v_pk_fma_f32 v[92:93], v[92:93], 0.5, v[104:105] op_sel_hi:[1,0,1]
	v_pk_fma_f32 v[90:91], v[90:91], 0.5, v[98:99] op_sel_hi:[1,0,1]
	v_pk_fma_f32 v[88:89], v[88:89], 0.5, v[106:107] op_sel_hi:[1,0,1]
	s_nop 1
	v_mov_b32_dpp v168, v88 row_ror:8 row_mask:0xf bank_mask:0xf
	v_mov_b32_dpp v169, v89 row_ror:8 row_mask:0xf bank_mask:0xf
	v_mov_b32_dpp v170, v90 row_ror:8 row_mask:0xf bank_mask:0xf
	v_mov_b32_dpp v171, v91 row_ror:8 row_mask:0xf bank_mask:0xf
	v_lshl_add_u64 v[180:181], v[100:101], 0, v[248:249]
	v_lshl_add_u64 v[182:183], v[100:101], 0, v[250:251]
	v_cndmask_b32_e64 v172, v168, v92, s[94:95]
	v_cndmask_b32_e64 v173, v169, v93, s[94:95]
	v_cndmask_b32_e64 v174, v170, v94, s[94:95]
	v_cndmask_b32_e64 v175, v171, v95, s[94:95]
	v_cndmask_b32_e64 v176, v92, v168, s[94:95]
	v_cndmask_b32_e64 v177, v93, v169, s[94:95]
	v_cndmask_b32_e64 v178, v94, v170, s[94:95]
	v_cndmask_b32_e64 v179, v95, v171, s[94:95]
	global_store_dwordx4 v[180:181], v[172:175], off
	global_store_dwordx4 v[182:183], v[176:179], off
	s_nop 1
	v_mov_b64_e32 v[88:89], v[204:205]
	v_mov_b64_e32 v[90:91], v[206:207]
	v_or_b32_e32 v92, 48, v148
	v_ashrrev_i32_e32 v93, 31, v92
	v_lshlrev_b64 v[92:93], 10, v[92:93]
	v_lshl_add_u64 v[92:93], v[92:93], 0, v[146:147]
	v_lshlrev_b64 v[94:95], 1, v[92:93]
	v_lshl_add_u64 v[96:97], s[46:47], 0, v[94:95]
	v_or_b32_e32 v94, 0x100, v94
	v_lshlrev_b32_e32 v98, 16, v88
	v_and_b32_e32 v99, 0xffff0000, v88
	v_lshlrev_b32_e32 v88, 16, v89
	v_and_b32_e32 v89, 0xffff0000, v89
	v_lshlrev_b32_e32 v102, 16, v90
	v_and_b32_e32 v103, 0xffff0000, v90
	v_lshlrev_b32_e32 v90, 16, v91
	v_and_b32_e32 v91, 0xffff0000, v91
	v_pk_fma_f32 v[86:87], v[86:87], 0.5, v[88:89] op_sel_hi:[1,0,1]
	v_pk_fma_f32 v[84:85], v[84:85], 0.5, v[98:99] op_sel_hi:[1,0,1]
	v_pk_fma_f32 v[82:83], v[82:83], 0.5, v[90:91] op_sel_hi:[1,0,1]
	v_pk_fma_f32 v[80:81], v[80:81], 0.5, v[102:103] op_sel_hi:[1,0,1]
;     __device__ __forceinline__ void operator()(const AccT& acc, const Unit& u, int wr, int wc, int fr, int fq) const {
;     ...
;                 const int row = row0 + ai * HALF + m * 16; float sq = 0.f;
; #pragma unroll
;                 for (int bj = 0; bj < 2; ++bj) {
;                     const size_t off = (size_t)row * DM + col0 + bj * HALF;
;                     f32x4 r0, r1;
;                     if (RES_BF16) { float f[8]; unpack8(*(const u32x4*)(resb + off), f); r0 = (f32x4){f[0], f[1], f[2], f[3]}; r1 = (f32x4){f[4], f[5], f[6], f[7]}; }
;                     else { r0 = *(const f32x4*)(res + off); r1 = *(const f32x4*)(res + off + 4); }
;                     const f32x4 v0 = r0 + acc[ai][bj][m][0] * alpha, v1 = r1 + acc[ai][bj][m][1] * alpha;
;                     if (WRITE_F32) { *(f32x4*)(out + off) = v0; *(f32x4*)(out + off + 4) = v1; }
	s_nop 1
	v_mov_b32_dpp v168, v80 row_ror:8 row_mask:0xf bank_mask:0xf
	v_mov_b32_dpp v169, v81 row_ror:8 row_mask:0xf bank_mask:0xf
	v_mov_b32_dpp v170, v82 row_ror:8 row_mask:0xf bank_mask:0xf
	v_mov_b32_dpp v171, v83 row_ror:8 row_mask:0xf bank_mask:0xf
	v_lshl_add_u64 v[180:181], v[100:101], 0, v[248:249]
	v_lshl_add_u64 v[182:183], v[100:101], 0, v[250:251]
	v_cndmask_b32_e64 v172, v168, v84, s[94:95]
	v_cndmask_b32_e64 v173, v169, v85, s[94:95]
	v_cndmask_b32_e64 v174, v170, v86, s[94:95]
	v_cndmask_b32_e64 v175, v171, v87, s[94:95]
	v_cndmask_b32_e64 v176, v84, v168, s[94:95]
	v_cndmask_b32_e64 v177, v85, v169, s[94:95]
	v_cndmask_b32_e64 v178, v86, v170, s[94:95]
	v_cndmask_b32_e64 v179, v87, v171, s[94:95]
	global_store_dwordx4 v[180:181], v[172:175], off offset:512
	global_store_dwordx4 v[182:183], v[176:179], off offset:512
	s_nop 1
	v_mov_b64_e32 v[80:81], v[208:209]
	v_mov_b64_e32 v[82:83], v[210:211]
	v_lshl_add_u64 v[84:85], v[92:93], 2, s[68:69]
	v_lshl_add_u64 v[86:87], s[46:47], 0, v[94:95]
	v_lshlrev_b32_e32 v88, 16, v80
	v_and_b32_e32 v89, 0xffff0000, v80
	v_lshlrev_b32_e32 v80, 16, v81
	v_and_b32_e32 v81, 0xffff0000, v81
	v_lshlrev_b32_e32 v90, 16, v82
	v_and_b32_e32 v91, 0xffff0000, v82
	v_lshlrev_b32_e32 v82, 16, v83
	v_and_b32_e32 v83, 0xffff0000, v83
	v_pk_fma_f32 v[78:79], v[78:79], 0.5, v[80:81] op_sel_hi:[1,0,1]
	v_pk_fma_f32 v[76:77], v[76:77], 0.5, v[88:89] op_sel_hi:[1,0,1]
	v_pk_fma_f32 v[74:75], v[74:75], 0.5, v[82:83] op_sel_hi:[1,0,1]
	v_pk_fma_f32 v[72:73], v[72:73], 0.5, v[90:91] op_sel_hi:[1,0,1]
	s_nop 1
	v_mov_b32_dpp v168, v72 row_ror:8 row_mask:0xf bank_mask:0xf
	v_mov_b32_dpp v169, v73 row_ror:8 row_mask:0xf bank_mask:0xf
	v_mov_b32_dpp v170, v74 row_ror:8 row_mask:0xf bank_mask:0xf
	v_mov_b32_dpp v171, v75 row_ror:8 row_mask:0xf bank_mask:0xf
	v_lshl_add_u64 v[180:181], v[84:85], 0, v[248:249]
	v_lshl_add_u64 v[182:183], v[84:85], 0, v[250:251]
	v_cndmask_b32_e64 v172, v168, v76, s[94:95]
	v_cndmask_b32_e64 v173, v169, v77, s[94:95]
	v_cndmask_b32_e64 v174, v170, v78, s[94:95]
	v_cndmask_b32_e64 v175, v171, v79, s[94:95]
	v_cndmask_b32_e64 v176, v76, v168, s[94:95]
	v_cndmask_b32_e64 v177, v77, v169, s[94:95]
	v_cndmask_b32_e64 v178, v78, v170, s[94:95]
	v_cndmask_b32_e64 v179, v79, v171, s[94:95]
	global_store_dwordx4 v[180:181], v[172:175], off
	global_store_dwordx4 v[182:183], v[176:179], off
	s_nop 1
	v_mov_b64_e32 v[72:73], v[212:213]
	v_mov_b64_e32 v[74:75], v[214:215]
	v_lshl_add_u64 v[76:77], v[144:145], 0, s[12:13]
	v_lshlrev_b64 v[78:79], 1, v[76:77]
	v_lshl_add_u64 v[80:81], s[46:47], 0, v[78:79]
	v_or_b32_e32 v78, 0x100, v78
	v_lshlrev_b32_e32 v82, 16, v72
	v_and_b32_e32 v83, 0xffff0000, v72
	v_lshlrev_b32_e32 v72, 16, v73
	v_and_b32_e32 v73, 0xffff0000, v73
	v_lshlrev_b32_e32 v86, 16, v74
	v_and_b32_e32 v87, 0xffff0000, v74
	v_lshlrev_b32_e32 v74, 16, v75
	v_and_b32_e32 v75, 0xffff0000, v75
	v_pk_fma_f32 v[70:71], v[70:71], 0.5, v[72:73] op_sel_hi:[1,0,1]
	v_pk_fma_f32 v[68:69], v[68:69], 0.5, v[82:83] op_sel_hi:[1,0,1]
	v_pk_fma_f32 v[66:67], v[66:67], 0.5, v[74:75] op_sel_hi:[1,0,1]
	v_pk_fma_f32 v[64:65], v[64:65], 0.5, v[86:87] op_sel_hi:[1,0,1]
	s_nop 1
	v_mov_b32_dpp v168, v64 row_ror:8 row_mask:0xf bank_mask:0xf
	v_mov_b32_dpp v169, v65 row_ror:8 row_mask:0xf bank_mask:0xf
	v_mov_b32_dpp v170, v66 row_ror:8 row_mask:0xf bank_mask:0xf
	v_mov_b32_dpp v171, v67 row_ror:8 row_mask:0xf bank_mask:0xf
	v_lshl_add_u64 v[180:181], v[84:85], 0, v[248:249]
	v_lshl_add_u64 v[182:183], v[84:85], 0, v[250:251]
	v_cndmask_b32_e64 v172, v168, v68, s[94:95]
	v_cndmask_b32_e64 v173, v169, v69, s[94:95]
	v_cndmask_b32_e64 v174, v170, v70, s[94:95]
	v_cndmask_b32_e64 v175, v171, v71, s[94:95]
	v_cndmask_b32_e64 v176, v68, v168, s[94:95]
	v_cndmask_b32_e64 v177, v69, v169, s[94:95]
	v_cndmask_b32_e64 v178, v70, v170, s[94:95]
	v_cndmask_b32_e64 v179, v71, v171, s[94:95]
	global_store_dwordx4 v[180:181], v[172:175], off offset:512
	global_store_dwordx4 v[182:183], v[176:179], off offset:512
	s_nop 1
	v_mov_b64_e32 v[64:65], v[216:217]
	v_mov_b64_e32 v[66:67], v[218:219]
	v_lshl_add_u64 v[68:69], v[76:77], 2, s[68:69]
	v_lshl_add_u64 v[70:71], s[46:47], 0, v[78:79]
	v_lshlrev_b32_e32 v72, 16, v64
	v_and_b32_e32 v73, 0xffff0000, v64
	v_lshlrev_b32_e32 v64, 16, v65
	v_and_b32_e32 v65, 0xffff0000, v65
	v_lshlrev_b32_e32 v74, 16, v66
	v_and_b32_e32 v75, 0xffff0000, v66
	v_lshlrev_b32_e32 v66, 16, v67
	v_and_b32_e32 v67, 0xffff0000, v67
	v_pk_fma_f32 v[62:63], v[62:63], 0.5, v[64:65] op_sel_hi:[1,0,1]
	v_pk_fma_f32 v[60:61], v[60:61], 0.5, v[72:73] op_sel_hi:[1,0,1]
	v_pk_fma_f32 v[58:59], v[58:59], 0.5, v[66:67] op_sel_hi:[1,0,1]
	v_pk_fma_f32 v[56:57], v[56:57], 0.5, v[74:75] op_sel_hi:[1,0,1]
	s_nop 1
	v_mov_b32_dpp v168, v56 row_ror:8 row_mask:0xf bank_mask:0xf
	v_mov_b32_dpp v169, v57 row_ror:8 row_mask:0xf bank_mask:0xf
	v_mov_b32_dpp v170, v58 row_ror:8 row_mask:0xf bank_mask:0xf
	v_mov_b32_dpp v171, v59 row_ror:8 row_mask:0xf bank_mask:0xf
	v_lshl_add_u64 v[180:181], v[68:69], 0, v[248:249]
	v_lshl_add_u64 v[182:183], v[68:69], 0, v[250:251]
	v_cndmask_b32_e64 v172, v168, v60, s[94:95]
	v_cndmask_b32_e64 v173, v169, v61, s[94:95]
	v_cndmask_b32_e64 v174, v170, v62, s[94:95]
	v_cndmask_b32_e64 v175, v171, v63, s[94:95]
	v_cndmask_b32_e64 v176, v60, v168, s[94:95]
	v_cndmask_b32_e64 v177, v61, v169, s[94:95]
	v_cndmask_b32_e64 v178, v62, v170, s[94:95]
	v_cndmask_b32_e64 v179, v63, v171, s[94:95]
	global_store_dwordx4 v[180:181], v[172:175], off
	global_store_dwordx4 v[182:183], v[176:179], off
	s_nop 1
	v_mov_b64_e32 v[56:57], v[220:221]
	v_mov_b64_e32 v[58:59], v[222:223]
;     __device__ __forceinline__ void operator()(const AccT& acc, const Unit& u, int wr, int wc, int fr, int fq) const {
;     ...
;                 const int row = row0 + ai * HALF + m * 16; float sq = 0.f;
; #pragma unroll
;                 for (int bj = 0; bj < 2; ++bj) {
;                     const size_t off = (size_t)row * DM + col0 + bj * HALF;
;                     f32x4 r0, r1;
;                     if (RES_BF16) { float f[8]; unpack8(*(const u32x4*)(resb + off), f); r0 = (f32x4){f[0], f[1], f[2], f[3]}; r1 = (f32x4){f[4], f[5], f[6], f[7]}; }
;                     else { r0 = *(const f32x4*)(res + off); r1 = *(const f32x4*)(res + off + 4); }
;                     const f32x4 v0 = r0 + acc[ai][bj][m][0] * alpha, v1 = r1 + acc[ai][bj][m][1] * alpha;
;                     if (WRITE_F32) { *(f32x4*)(out + off) = v0; *(f32x4*)(out + off + 4) = v1; }
	v_lshl_add_u64 v[60:61], v[144:145], 0, s[14:15]
	v_lshlrev_b64 v[62:63], 1, v[60:61]
	v_lshl_add_u64 v[64:65], s[46:47], 0, v[62:63]
	v_or_b32_e32 v62, 0x100, v62
	v_lshlrev_b32_e32 v66, 16, v56
	v_and_b32_e32 v67, 0xffff0000, v56
	v_lshlrev_b32_e32 v56, 16, v57
	v_and_b32_e32 v57, 0xffff0000, v57
	v_lshlrev_b32_e32 v70, 16, v58
	v_and_b32_e32 v71, 0xffff0000, v58
	v_lshlrev_b32_e32 v58, 16, v59
	v_and_b32_e32 v59, 0xffff0000, v59
	v_pk_fma_f32 v[54:55], v[54:55], 0.5, v[56:57] op_sel_hi:[1,0,1]
	v_pk_fma_f32 v[52:53], v[52:53], 0.5, v[66:67] op_sel_hi:[1,0,1]
	v_pk_fma_f32 v[50:51], v[50:51], 0.5, v[58:59] op_sel_hi:[1,0,1]
	v_pk_fma_f32 v[48:49], v[48:49], 0.5, v[70:71] op_sel_hi:[1,0,1]
	s_nop 1
	v_mov_b32_dpp v168, v48 row_ror:8 row_mask:0xf bank_mask:0xf
	v_mov_b32_dpp v169, v49 row_ror:8 row_mask:0xf bank_mask:0xf
	v_mov_b32_dpp v170, v50 row_ror:8 row_mask:0xf bank_mask:0xf
	v_mov_b32_dpp v171, v51 row_ror:8 row_mask:0xf bank_mask:0xf
	v_lshl_add_u64 v[180:181], v[68:69], 0, v[248:249]
	v_lshl_add_u64 v[182:183], v[68:69], 0, v[250:251]
	v_cndmask_b32_e64 v172, v168, v52, s[94:95]
	v_cndmask_b32_e64 v173, v169, v53, s[94:95]
	v_cndmask_b32_e64 v174, v170, v54, s[94:95]
	v_cndmask_b32_e64 v175, v171, v55, s[94:95]
	v_cndmask_b32_e64 v176, v52, v168, s[94:95]
	v_cndmask_b32_e64 v177, v53, v169, s[94:95]
	v_cndmask_b32_e64 v178, v54, v170, s[94:95]
	v_cndmask_b32_e64 v179, v55, v171, s[94:95]
	global_store_dwordx4 v[180:181], v[172:175], off offset:512
	global_store_dwordx4 v[182:183], v[176:179], off offset:512
	s_nop 1
	v_mov_b64_e32 v[48:49], v[224:225]
	v_mov_b64_e32 v[50:51], v[226:227]
	v_lshl_add_u64 v[52:53], v[60:61], 2, s[68:69]
	v_lshl_add_u64 v[54:55], s[46:47], 0, v[62:63]
	v_lshlrev_b32_e32 v56, 16, v48
	v_and_b32_e32 v57, 0xffff0000, v48
	v_lshlrev_b32_e32 v48, 16, v49
	v_and_b32_e32 v49, 0xffff0000, v49
	v_lshlrev_b32_e32 v58, 16, v50
	v_and_b32_e32 v59, 0xffff0000, v50
	v_lshlrev_b32_e32 v50, 16, v51
	v_and_b32_e32 v51, 0xffff0000, v51
	v_pk_fma_f32 v[46:47], v[46:47], 0.5, v[48:49] op_sel_hi:[1,0,1]
	v_pk_fma_f32 v[44:45], v[44:45], 0.5, v[56:57] op_sel_hi:[1,0,1]
	v_pk_fma_f32 v[42:43], v[42:43], 0.5, v[50:51] op_sel_hi:[1,0,1]
	v_pk_fma_f32 v[40:41], v[40:41], 0.5, v[58:59] op_sel_hi:[1,0,1]
	s_nop 1
	v_mov_b32_dpp v168, v40 row_ror:8 row_mask:0xf bank_mask:0xf
	v_mov_b32_dpp v169, v41 row_ror:8 row_mask:0xf bank_mask:0xf
	v_mov_b32_dpp v170, v42 row_ror:8 row_mask:0xf bank_mask:0xf
	v_mov_b32_dpp v171, v43 row_ror:8 row_mask:0xf bank_mask:0xf
	v_lshl_add_u64 v[180:181], v[52:53], 0, v[248:249]
	v_lshl_add_u64 v[182:183], v[52:53], 0, v[250:251]
	v_cndmask_b32_e64 v172, v168, v44, s[94:95]
	v_cndmask_b32_e64 v173, v169, v45, s[94:95]
	v_cndmask_b32_e64 v174, v170, v46, s[94:95]
	v_cndmask_b32_e64 v175, v171, v47, s[94:95]
	v_cndmask_b32_e64 v176, v44, v168, s[94:95]
	v_cndmask_b32_e64 v177, v45, v169, s[94:95]
	v_cndmask_b32_e64 v178, v46, v170, s[94:95]
	v_cndmask_b32_e64 v179, v47, v171, s[94:95]
	global_store_dwordx4 v[180:181], v[172:175], off
	global_store_dwordx4 v[182:183], v[176:179], off
	s_nop 1
	v_mov_b64_e32 v[40:41], v[228:229]
	v_mov_b64_e32 v[42:43], v[230:231]
	v_lshl_add_u64 v[44:45], v[144:145], 0, s[16:17]
	v_lshlrev_b64 v[46:47], 1, v[44:45]
	v_lshl_add_u64 v[48:49], s[46:47], 0, v[46:47]
	v_or_b32_e32 v46, 0x100, v46
	v_lshlrev_b32_e32 v50, 16, v40
	v_and_b32_e32 v51, 0xffff0000, v40
	v_lshlrev_b32_e32 v40, 16, v41
	v_and_b32_e32 v41, 0xffff0000, v41
	v_lshlrev_b32_e32 v54, 16, v42
	v_and_b32_e32 v55, 0xffff0000, v42
	v_lshlrev_b32_e32 v42, 16, v43
	v_and_b32_e32 v43, 0xffff0000, v43
	v_pk_fma_f32 v[38:39], v[38:39], 0.5, v[40:41] op_sel_hi:[1,0,1]
	v_pk_fma_f32 v[36:37], v[36:37], 0.5, v[50:51] op_sel_hi:[1,0,1]
	v_pk_fma_f32 v[34:35], v[34:35], 0.5, v[42:43] op_sel_hi:[1,0,1]
	v_pk_fma_f32 v[32:33], v[32:33], 0.5, v[54:55] op_sel_hi:[1,0,1]
	s_nop 1
	v_mov_b32_dpp v168, v32 row_ror:8 row_mask:0xf bank_mask:0xf
	v_mov_b32_dpp v169, v33 row_ror:8 row_mask:0xf bank_mask:0xf
	v_mov_b32_dpp v170, v34 row_ror:8 row_mask:0xf bank_mask:0xf
	v_mov_b32_dpp v171, v35 row_ror:8 row_mask:0xf bank_mask:0xf
	v_lshl_add_u64 v[180:181], v[52:53], 0, v[248:249]
	v_lshl_add_u64 v[182:183], v[52:53], 0, v[250:251]
	v_cndmask_b32_e64 v172, v168, v36, s[94:95]
	v_cndmask_b32_e64 v173, v169, v37, s[94:95]
	v_cndmask_b32_e64 v174, v170, v38, s[94:95]
	v_cndmask_b32_e64 v175, v171, v39, s[94:95]
	v_cndmask_b32_e64 v176, v36, v168, s[94:95]
	v_cndmask_b32_e64 v177, v37, v169, s[94:95]
	v_cndmask_b32_e64 v178, v38, v170, s[94:95]
	v_cndmask_b32_e64 v179, v39, v171, s[94:95]
	global_store_dwordx4 v[180:181], v[172:175], off offset:512
	global_store_dwordx4 v[182:183], v[176:179], off offset:512
	s_nop 1
	v_mov_b64_e32 v[32:33], v[232:233]
	v_mov_b64_e32 v[34:35], v[234:235]
	v_lshl_add_u64 v[36:37], v[44:45], 2, s[68:69]
	v_lshl_add_u64 v[38:39], s[46:47], 0, v[46:47]
	v_lshlrev_b32_e32 v40, 16, v32
	v_and_b32_e32 v41, 0xffff0000, v32
	v_lshlrev_b32_e32 v32, 16, v33
	v_and_b32_e32 v33, 0xffff0000, v33
	v_lshlrev_b32_e32 v42, 16, v34
	v_and_b32_e32 v43, 0xffff0000, v34
	v_lshlrev_b32_e32 v34, 16, v35
	v_and_b32_e32 v35, 0xffff0000, v35
	v_pk_fma_f32 v[30:31], v[30:31], 0.5, v[32:33] op_sel_hi:[1,0,1]
	v_pk_fma_f32 v[28:29], v[28:29], 0.5, v[40:41] op_sel_hi:[1,0,1]
	v_pk_fma_f32 v[26:27], v[26:27], 0.5, v[34:35] op_sel_hi:[1,0,1]
	v_pk_fma_f32 v[24:25], v[24:25], 0.5, v[42:43] op_sel_hi:[1,0,1]
	s_nop 1
	v_mov_b32_dpp v168, v24 row_ror:8 row_mask:0xf bank_mask:0xf
;     __device__ __forceinline__ void operator()(const AccT& acc, const Unit& u, int wr, int wc, int fr, int fq) const {
;     ...
;                 const int row = row0 + ai * HALF + m * 16; float sq = 0.f;
; #pragma unroll
;                 for (int bj = 0; bj < 2; ++bj) {
;                     const size_t off = (size_t)row * DM + col0 + bj * HALF;
;                     f32x4 r0, r1;
;                     if (RES_BF16) { float f[8]; unpack8(*(const u32x4*)(resb + off), f); r0 = (f32x4){f[0], f[1], f[2], f[3]}; r1 = (f32x4){f[4], f[5], f[6], f[7]}; }
;                     else { r0 = *(const f32x4*)(res + off); r1 = *(const f32x4*)(res + off + 4); }
;                     const f32x4 v0 = r0 + acc[ai][bj][m][0] * alpha, v1 = r1 + acc[ai][bj][m][1] * alpha;
;                     if (WRITE_F32) { *(f32x4*)(out + off) = v0; *(f32x4*)(out + off + 4) = v1; }
	v_mov_b32_dpp v169, v25 row_ror:8 row_mask:0xf bank_mask:0xf
	v_mov_b32_dpp v170, v26 row_ror:8 row_mask:0xf bank_mask:0xf
	v_mov_b32_dpp v171, v27 row_ror:8 row_mask:0xf bank_mask:0xf
	v_lshl_add_u64 v[180:181], v[36:37], 0, v[248:249]
	v_lshl_add_u64 v[182:183], v[36:37], 0, v[250:251]
	v_cndmask_b32_e64 v172, v168, v28, s[94:95]
	v_cndmask_b32_e64 v173, v169, v29, s[94:95]
	v_cndmask_b32_e64 v174, v170, v30, s[94:95]
	v_cndmask_b32_e64 v175, v171, v31, s[94:95]
	v_cndmask_b32_e64 v176, v28, v168, s[94:95]
	v_cndmask_b32_e64 v177, v29, v169, s[94:95]
	v_cndmask_b32_e64 v178, v30, v170, s[94:95]
	v_cndmask_b32_e64 v179, v31, v171, s[94:95]
	global_store_dwordx4 v[180:181], v[172:175], off
	global_store_dwordx4 v[182:183], v[176:179], off
	s_nop 1
	v_mov_b64_e32 v[24:25], v[236:237]
	v_mov_b64_e32 v[26:27], v[238:239]
	v_lshl_add_u64 v[28:29], v[144:145], 0, s[18:19]
	v_lshlrev_b64 v[30:31], 1, v[28:29]
	v_lshl_add_u64 v[32:33], s[46:47], 0, v[30:31]
	v_or_b32_e32 v30, 0x100, v30
	v_lshlrev_b32_e32 v34, 16, v24
	v_and_b32_e32 v35, 0xffff0000, v24
	v_lshlrev_b32_e32 v24, 16, v25
	v_and_b32_e32 v25, 0xffff0000, v25
	v_lshlrev_b32_e32 v38, 16, v26
	v_and_b32_e32 v39, 0xffff0000, v26
	v_lshlrev_b32_e32 v26, 16, v27
	v_and_b32_e32 v27, 0xffff0000, v27
	v_pk_fma_f32 v[22:23], v[22:23], 0.5, v[24:25] op_sel_hi:[1,0,1]
	v_pk_fma_f32 v[20:21], v[20:21], 0.5, v[34:35] op_sel_hi:[1,0,1]
	v_pk_fma_f32 v[18:19], v[18:19], 0.5, v[26:27] op_sel_hi:[1,0,1]
	v_pk_fma_f32 v[16:17], v[16:17], 0.5, v[38:39] op_sel_hi:[1,0,1]
	s_nop 1
	v_mov_b32_dpp v168, v16 row_ror:8 row_mask:0xf bank_mask:0xf
	v_mov_b32_dpp v169, v17 row_ror:8 row_mask:0xf bank_mask:0xf
	v_mov_b32_dpp v170, v18 row_ror:8 row_mask:0xf bank_mask:0xf
	v_mov_b32_dpp v171, v19 row_ror:8 row_mask:0xf bank_mask:0xf
	v_lshl_add_u64 v[180:181], v[36:37], 0, v[248:249]
	v_lshl_add_u64 v[182:183], v[36:37], 0, v[250:251]
	v_cndmask_b32_e64 v172, v168, v20, s[94:95]
	v_cndmask_b32_e64 v173, v169, v21, s[94:95]
	v_cndmask_b32_e64 v174, v170, v22, s[94:95]
	v_cndmask_b32_e64 v175, v171, v23, s[94:95]
	v_cndmask_b32_e64 v176, v20, v168, s[94:95]
	v_cndmask_b32_e64 v177, v21, v169, s[94:95]
	v_cndmask_b32_e64 v178, v22, v170, s[94:95]
	v_cndmask_b32_e64 v179, v23, v171, s[94:95]
	global_store_dwordx4 v[180:181], v[172:175], off offset:512
	global_store_dwordx4 v[182:183], v[176:179], off offset:512
	s_nop 1
	v_mov_b64_e32 v[16:17], v[240:241]
	v_mov_b64_e32 v[18:19], v[242:243]
	v_lshl_add_u64 v[20:21], v[28:29], 2, s[68:69]
	v_lshl_add_u64 v[22:23], s[46:47], 0, v[30:31]
	v_lshlrev_b32_e32 v24, 16, v16
	v_and_b32_e32 v25, 0xffff0000, v16
	v_lshlrev_b32_e32 v16, 16, v17
	v_and_b32_e32 v17, 0xffff0000, v17
	v_lshlrev_b32_e32 v26, 16, v18
	v_and_b32_e32 v27, 0xffff0000, v18
	v_lshlrev_b32_e32 v18, 16, v19
	v_and_b32_e32 v19, 0xffff0000, v19
	v_pk_fma_f32 v[14:15], v[14:15], 0.5, v[16:17] op_sel_hi:[1,0,1]
	v_pk_fma_f32 v[12:13], v[12:13], 0.5, v[24:25] op_sel_hi:[1,0,1]
	v_pk_fma_f32 v[10:11], v[10:11], 0.5, v[18:19] op_sel_hi:[1,0,1]
	v_pk_fma_f32 v[8:9], v[8:9], 0.5, v[26:27] op_sel_hi:[1,0,1]
	s_nop 1
	v_mov_b32_dpp v168, v8 row_ror:8 row_mask:0xf bank_mask:0xf
	v_mov_b32_dpp v169, v9 row_ror:8 row_mask:0xf bank_mask:0xf
	v_mov_b32_dpp v170, v10 row_ror:8 row_mask:0xf bank_mask:0xf
	v_mov_b32_dpp v171, v11 row_ror:8 row_mask:0xf bank_mask:0xf
	v_lshl_add_u64 v[180:181], v[20:21], 0, v[248:249]
	v_lshl_add_u64 v[182:183], v[20:21], 0, v[250:251]
	v_cndmask_b32_e64 v172, v168, v12, s[94:95]
	v_cndmask_b32_e64 v173, v169, v13, s[94:95]
	v_cndmask_b32_e64 v174, v170, v14, s[94:95]
	v_cndmask_b32_e64 v175, v171, v15, s[94:95]
	v_cndmask_b32_e64 v176, v12, v168, s[94:95]
	v_cndmask_b32_e64 v177, v13, v169, s[94:95]
	v_cndmask_b32_e64 v178, v14, v170, s[94:95]
	v_cndmask_b32_e64 v179, v15, v171, s[94:95]
	global_store_dwordx4 v[180:181], v[172:175], off
	global_store_dwordx4 v[182:183], v[176:179], off
	s_nop 1
	v_mov_b64_e32 v[8:9], v[244:245]
	v_mov_b64_e32 v[10:11], v[246:247]
	v_lshlrev_b32_e32 v12, 16, v8
	v_and_b32_e32 v13, 0xffff0000, v8
	v_lshlrev_b32_e32 v8, 16, v9
	v_and_b32_e32 v9, 0xffff0000, v9
	v_lshlrev_b32_e32 v14, 16, v10
	v_and_b32_e32 v15, 0xffff0000, v10
	v_lshlrev_b32_e32 v10, 16, v11
	v_and_b32_e32 v11, 0xffff0000, v11
	v_pk_fma_f32 v[6:7], v[6:7], 0.5, v[8:9] op_sel_hi:[1,0,1]
	v_pk_fma_f32 v[4:5], v[4:5], 0.5, v[12:13] op_sel_hi:[1,0,1]
	v_pk_fma_f32 v[2:3], v[2:3], 0.5, v[10:11] op_sel_hi:[1,0,1]
	v_pk_fma_f32 v[0:1], v[0:1], 0.5, v[14:15] op_sel_hi:[1,0,1]
	s_nop 1
	v_mov_b32_dpp v168, v0 row_ror:8 row_mask:0xf bank_mask:0xf
	v_mov_b32_dpp v169, v1 row_ror:8 row_mask:0xf bank_mask:0xf
	v_mov_b32_dpp v170, v2 row_ror:8 row_mask:0xf bank_mask:0xf
	v_mov_b32_dpp v171, v3 row_ror:8 row_mask:0xf bank_mask:0xf
	v_lshl_add_u64 v[180:181], v[20:21], 0, v[248:249]
	v_lshl_add_u64 v[182:183], v[20:21], 0, v[250:251]
	v_cndmask_b32_e64 v172, v168, v4, s[94:95]
	v_cndmask_b32_e64 v173, v169, v5, s[94:95]
	v_cndmask_b32_e64 v174, v170, v6, s[94:95]
	v_cndmask_b32_e64 v175, v171, v7, s[94:95]
	v_cndmask_b32_e64 v176, v4, v168, s[94:95]
	v_cndmask_b32_e64 v177, v5, v169, s[94:95]
	v_cndmask_b32_e64 v178, v6, v170, s[94:95]
	v_cndmask_b32_e64 v179, v7, v171, s[94:95]
	global_store_dwordx4 v[180:181], v[172:175], off offset:512
	global_store_dwordx4 v[182:183], v[176:179], off offset:512
	s_cbranch_vccnz .LBB0_1626
	s_andn2_b64 vcc, exec, s[6:7]
	s_cbranch_vccnz .LBB0_1625
	s_barrier
	s_branch .LBB0_1625
